# v96 with the F1 prep hand-written: log-decay pre-scaled by log2e before the scans, exp2(+-lam), exp(lam-lw) taken from the previous token by a one-lane wave shift, unpack/multiply/convert batched for
# baseline (speedup 1.0000x reference)
.LBB0_865:
	s_andn2_b64 vcc, exec, s[8:9]
	s_cbranch_vccnz .LBB0_911
	v_writelane_b32 v254, s24, 44
	s_ashr_i32 s8, s18, 1
	s_lshl_b32 s12, s18, 3
	v_writelane_b32 v254, s25, 45
	s_and_b32 s20, s18, 3
	s_and_b32 s9, s8, -2
	s_lshl_b32 s17, s18, 5
	s_lshl_b32 s22, s18, 4
	v_writelane_b32 v254, s12, 46
	s_ashr_i32 s12, s12, 31
	v_writelane_b32 v254, s12, 47
	s_add_u32 s12, s36, 0x16600000
	s_addc_u32 s13, s37, 0
	v_writelane_b32 v254, s12, 48
	v_lshrrev_b32_e32 v2, 4, v114
	v_and_b32_e32 v28, 15, v1
	v_writelane_b32 v254, s13, 49
	s_add_u32 s12, s36, 0x32380000
	v_writelane_b32 v254, s12, 50
	s_addc_u32 s12, s37, 0
	v_writelane_b32 v254, s12, 51
	s_add_u32 s12, s36, 0x3a780000
	s_addc_u32 s13, s37, 0
	v_writelane_b32 v254, s12, 52
	v_lshlrev_b32_e32 v32, 2, v2
	v_lshlrev_b32_e32 v34, 3, v2
	v_writelane_b32 v254, s13, 53
	s_add_u32 s12, s36, 0x18700000
	s_addc_u32 s13, s37, 0
	v_writelane_b32 v254, s12, 54
	v_lshl_or_b32 v43, s8, 4, v28
	v_mul_lo_u32 v44, v43, s76
	v_writelane_b32 v254, s13, 55
	s_add_u32 s12, s36, 0x36580000
	v_writelane_b32 v254, s12, 56
	s_addc_u32 s12, s37, 0
	v_writelane_b32 v254, s12, 57
	s_add_u32 s12, s36, 0x29f80000
	v_writelane_b32 v254, s12, 58
	s_addc_u32 s12, s37, 0
	s_cmp_le_i32 s9, s20
	s_cselect_b64 s[28:29], -1, 0
	s_or_b32 s21, s8, 1
	v_writelane_b32 v254, s12, 59
	s_cmp_le_i32 s21, s20
	s_cselect_b64 s[24:25], -1, 0
	s_lshl_b32 s12, s20, 4
	s_lshl_b32 s19, s20, 5
	v_readlane_b32 s26, v254, 32
	v_or_b32_e32 v30, s12, v28
	v_or_b32_e32 v33, s12, v32
	s_add_i32 s12, s26, s19
	v_add_u32_e32 v119, s12, v34
	v_readlane_b32 s12, v254, 33
	v_readlane_b32 s34, v254, 37
	s_add_i32 s23, 0, 0x12000
	v_mov_b32_e32 v35, s12
	v_readlane_b32 s12, v254, 34
	s_waitcnt vmcnt(0)
	v_mad_u32_u24 v120, v30, s76, v35
	v_mul_u32_u24_e32 v31, 0x90, v30
	v_mov_b32_e32 v35, s12
	v_readlane_b32 s12, v254, 35
	v_mad_u32_u24 v122, v30, s76, v35
	v_readlane_b32 s27, v254, 36
	v_mov_b32_e32 v35, s12
	s_add_i32 s12, s34, s19
	v_add_u32_e32 v129, s12, v34
	s_and_b32 s12, s18, 2
	s_cmp_eq_u32 s9, s12
	s_cselect_b64 s[40:41], -1, 0
	s_cmp_lt_i32 s18, 2
	v_add3_u32 v118, s23, v31, v34
	v_add3_u32 v126, s27, v31, v34
	v_bfe_u32 v31, v1, 2, 2
	s_cselect_b64 s[42:43], -1, 0
	s_cmp_eq_u32 s18, 0
	v_mad_u32_u24 v124, v30, s76, v35
	v_or_b32_e32 v35, v34, v31
	s_cselect_b32 s12, 16, 48
	s_cselect_b32 s13, 0, 64
	v_or3_b32 v31, s17, v31, v34
	v_mul_lo_u32 v31, v31, s76
	s_add_i32 s16, s13, 0
	v_or_b32_e32 v39, s12, v28
	s_lshl_b32 s12, s18, 6
	v_add_u32_e32 v31, s16, v31
	s_add_i32 s16, s12, s23
	v_mov_b32_e32 v40, s16
	v_mad_u32_u24 v40, v39, s76, v40
	v_mad_u32_u24 v39, v39, s76, 0
	s_cmp_lt_i32 s18, 4
	v_add_u32_e32 v41, s13, v39
	v_add_u32_e32 v39, s12, v39
	s_cselect_b64 s[12:13], -1, 0
	s_and_b32 s16, s17, 32
	v_add_u32_e32 v44, 0x1200, v44
	v_mad_u32_u24 v35, v35, s76, 0
	v_add_u32_e32 v130, 0, v44
	s_cmp_gt_u32 s20, 1
	v_lshlrev_b32_e32 v36, 3, v1
	v_writelane_b32 v254, s17, 60
	v_add_u32_e32 v42, s16, v35
	v_add_u32_e32 v45, s23, v44
	v_add_u32_e32 v44, s16, v130
	s_cselect_b64 s[16:17], -1, 0
	s_add_i32 s8, s23, s19
	v_mad_u32_u24 v116, v30, s76, 0
	v_and_b32_e32 v36, 24, v36
	v_add_u32_e32 v132, s8, v34
	s_add_i32 s8, s27, s19
	v_and_b32_e32 v117, 48, v1
	v_add_u32_e32 v128, v35, v36
	v_or_b32_e32 v37, s19, v34
	v_add_u32_e32 v38, s19, v116
	v_add_u32_e32 v133, s8, v34
	v_add_u32_e32 v35, s19, v35
	v_readlane_b32 s19, v254, 38
	s_lshl_b32 s8, s20, 6
	v_lshlrev_b32_e32 v1, 1, v1
	s_add_i32 s8, s19, s8
	v_and_b32_e32 v46, 48, v114
	v_and_b32_e32 v1, 0x60, v1
	v_add_u32_e32 v135, s8, v46
	s_and_b32 s8, s18, 0xffffffc
	v_lshl_or_b32 v1, s20, 3, v1
	v_or_b32_e32 v46, s8, v2
	v_add_u32_e32 v136, s26, v1
	v_add_u32_e32 v137, 0, v1
	v_lshrrev_b32_e32 v1, 3, v0
	s_mov_b32 s8, 0xffffff0
	v_and_or_b32 v1, v1, s8, v28
	s_lshl_b32 s8, s9, 4
	s_lshl_b32 s30, s9, 5
	v_bfe_u32 v47, v0, 6, 1
	v_lshlrev_b32_e32 v104, 4, v0
	v_or_b32_e32 v0, s8, v28
	v_or_b32_e32 v48, 2, v33
	v_or_b32_e32 v49, 3, v33
	s_cmp_lg_u32 s9, s20
	v_lshl_add_u32 v134, v30, 2, s19
	v_mul_lo_u32 v140, v0, s76
	v_cmp_lt_i32_e64 s[44:45], v0, v33
	v_cmp_gt_i32_e64 s[46:47], v0, v33
	v_cmp_lt_i32_e64 s[18:19], v0, v48
	v_cmp_lt_i32_e64 s[62:63], v0, v49
	v_or_b32_e32 v0, s8, v32
	s_cselect_b64 s[64:65], -1, 0
	s_lshl_b32 s8, s21, 4
	v_or_b32_e32 v50, 1, v0
	v_cmp_eq_u32_e32 vcc, v0, v30
	v_or_b32_e32 v28, s8, v28
	v_cmp_lt_i32_e64 s[52:53], v50, v30
	v_cndmask_b32_e64 v106, 0, 1.0, vcc
	v_cmp_eq_u32_e32 vcc, v50, v30
	v_or_b32_e32 v50, 3, v0
	v_cmp_lt_i32_e64 s[70:71], v28, v48
	v_cndmask_b32_e64 v107, 0, 1.0, vcc
	v_or_b32_e32 v51, 2, v0
	v_cmp_eq_u32_e32 vcc, v50, v30
	v_writelane_b32 v254, s70, 61
	v_cmp_lt_i32_e64 s[66:67], v28, v33
	v_cndmask_b32_e64 v109, 0, 1.0, vcc
	v_cmp_eq_u32_e32 vcc, v51, v30
	v_cmp_gt_i32_e64 s[68:69], v28, v33
	v_writelane_b32 v254, s71, 62
	v_cmp_lt_i32_e64 s[70:71], v28, v49
	v_mul_lo_u32 v141, v28, s76
	v_or_b32_e32 v28, s8, v32
	v_cndmask_b32_e64 v108, 0, 1.0, vcc
	v_or_b32_e32 v32, 1, v28
	v_cmp_eq_u32_e32 vcc, v28, v30
	v_or_b32_e32 v43, 16, v43
	v_cmp_lt_i32_e64 s[74:75], v32, v30
	v_cndmask_b32_e64 v110, 0, 1.0, vcc
	v_cmp_eq_u32_e32 vcc, v32, v30
	v_or_b32_e32 v32, 3, v28
	v_lshlrev_b32_e32 v2, 5, v2
	v_mul_lo_u32 v1, v1, s76
	v_mul_lo_u32 v43, v43, s76
	v_writelane_b32 v254, s70, 63
	s_lshl_b32 s31, s21, 5
	v_cndmask_b32_e64 v111, 0, 1.0, vcc
	v_or_b32_e32 v33, 2, v28
	v_cmp_eq_u32_e32 vcc, v32, v30
	v_mad_u32_u24 v29, v114, s76, 0
	v_mad_u32_u24 v37, v30, s76, v37
	v_lshlrev_b32_e32 v46, 4, v46
	v_lshl_or_b32 v138, v47, 4, v2
	v_add_u32_e32 v139, 0, v1
	v_lshl_or_b32 v2, v47, 6, v117
	v_add_u32_e32 v1, s26, v1
	v_add_u32_e32 v47, 0, v140
	v_add_u32_e32 v43, 0, v43
	v_cmp_lt_i32_e64 s[48:49], v0, v30
	v_cmp_gt_i32_e64 s[50:51], v0, v30
	v_cmp_lt_i32_e64 s[54:55], v51, v30
	v_cmp_gt_i32_e64 s[56:57], v51, v30
	v_cmp_lt_i32_e64 s[58:59], v50, v30
	v_cmp_gt_i32_e64 s[60:61], v50, v30
	v_writelane_b32 v255, s71, 0
	v_cmp_lt_i32_e64 s[70:71], v28, v30
	v_cmp_gt_i32_e64 s[72:73], v28, v30
	v_cndmask_b32_e64 v113, 0, 1.0, vcc
	v_cmp_eq_u32_e32 vcc, v33, v30
	v_cmp_lt_i32_e64 s[76:77], v33, v30
	s_cmp_lg_u32 s21, s20
	v_cmp_gt_i32_e64 s[78:79], v33, v30
	v_add_u32_e32 v33, s23, v140
	v_add_u32_e32 v48, s23, v141
	v_add_u32_e32 v49, s34, v140
	v_add_u32_e32 v50, s34, v141
	v_add_u32_e32 v51, s27, v140
	v_lshlrev_b32_e32 v0, 1, v0
	v_add_u32_e32 v52, s27, v141
	v_lshlrev_b32_e32 v28, 1, v28
	v_cmp_ne_u32_e64 s[38:39], 63, v114
	v_xor_b32_e32 v115, 63, v114
	v_add_u32_e32 v121, v120, v34
	v_add_u32_e32 v123, v122, v34
	v_add_u32_e32 v125, v124, v34
	v_add_u32_e32 v127, v116, v34
	v_add_u32_e32 v131, s34, v117
	v_ashrrev_i32_e32 v105, 31, v104
	v_cndmask_b32_e64 v112, 0, 1.0, vcc
	s_cselect_b64 s[20:21], -1, 0
	v_add_u32_e32 v142, s22, v29
	s_lshl_b32 s26, s90, 6
	v_add_u32_e32 v143, v47, v117
	v_add_u32_e32 v144, v43, v117
	v_add_u32_e32 v145, 0, v37
	v_add_u32_e32 v146, v38, v34
	v_add_u32_e32 v147, v31, v36
	v_add_u32_e32 v148, v40, v117
	v_add_u32_e32 v149, v41, v34
	v_add_u32_e32 v150, v39, v117
	v_add_u32_e32 v151, v45, v117
	v_add_u32_e32 v152, v49, v117
	v_add_u32_e32 v153, v50, v117
	v_add_u32_e32 v154, v35, v36
	v_add_u32_e32 v155, v51, v117
	v_add_u32_e32 v156, v33, v117
	v_add_u32_e32 v157, v116, v0
	v_add_u32_e32 v158, v52, v117
	v_add_u32_e32 v159, v48, v117
	v_add_u32_e32 v160, v116, v28
	v_add_u32_e32 v161, v139, v2
	v_add_u32_e32 v162, v1, v138
	v_add_u32_e32 v163, v42, v36
	v_add_u32_e32 v164, v44, v34
	v_add_u32_e32 v165, v116, v46
	s_sub_i32 s27, 0x82, s90
	v_cmp_lt_i32_e64 s[80:81], v32, v30
	v_cmp_gt_i32_e64 s[82:83], v32, v30
	v_mov_b32_e32 v212, 1.0
	v_mov_b32_e32 v213, 1.0
	v_mov_b32_e32 v214, 1.0
	v_mov_b32_e32 v215, 1.0
	v_mov_b32_e32 v216, 1.0
	v_mov_b32_e32 v217, 1.0
	v_mov_b32_e32 v218, 1.0
	v_mov_b32_e32 v219, 1.0
	v_add_u32_e32 v166, v116, v117
	v_add_u32_e32 v167, s30, v118
	v_add_u32_e32 v168, v119, v140
	v_add_u32_e32 v169, s30, v121
	v_add_u32_e32 v170, s30, v123
	v_add_u32_e32 v171, s30, v126
	v_add_u32_e32 v172, s30, v125
	v_add_u32_e32 v173, s30, v127
	v_add_u32_e32 v174, s31, v118
	v_add_u32_e32 v175, v119, v141
	v_add_u32_e32 v176, s31, v121
	v_add_u32_e32 v177, s31, v123
	v_add_u32_e32 v178, s31, v126
	v_add_u32_e32 v179, s31, v125
	v_add_u32_e32 v182, s31, v127
	v_add_u32_e32 v183, v120, v117
	v_add_u32_e32 v184, s30, v128
	v_add_u32_e32 v185, s31, v128
	v_add_u32_e32 v186, v129, v140
	v_add_u32_e32 v187, v129, v141
	v_add_u32_e32 v188, 0x14400, v145
	v_add_u32_e32 v189, 0x16800, v145
	v_add_u32_e32 v190, v130, v117
	v_add_u32_e32 v191, v131, v140
	v_add_u32_e32 v192, v131, v141
	v_add_u32_e32 v193, v132, v140
	v_add_u32_e32 v194, v133, v140
	v_add_u32_e32 v195, v132, v141
	v_add_u32_e32 v196, v133, v141
	v_add_u32_e32 v197, v124, v117
	v_add_u32_e32 v200, v122, v117
	v_add_u32_e32 v201, v137, v140
	v_add_u32_e32 v204, v136, v141
	v_add_u32_e32 v205, 8, v165
	v_add_u32_e32 v206, v137, v141
	v_add_u32_e32 v207, v139, v138
.LBB0_867:
	s_waitcnt vmcnt(4)
	v_cvt_f32_f16 v28, v24
	v_lshrrev_b32_e32 v0, 16, v24
	v_cvt_f32_f16 v29, v0
	v_cvt_f32_f16 v30, v25
	v_lshrrev_b32_e32 v0, 16, v25
	v_cvt_f32_f16 v31, v0
	v_cvt_f32_f16 v32, v26
	v_lshrrev_b32_e32 v0, 16, v26
	v_cvt_f32_f16 v33, v0
	v_cvt_f32_f16 v34, v27
	v_lshrrev_b32_e32 v0, 16, v27
	v_cvt_f32_f16 v35, v0
	v_mul_f32_e32 v28, 0x3fb8aa3b, v28
	v_mul_f32_e32 v29, 0x3fb8aa3b, v29
	v_mul_f32_e32 v30, 0x3fb8aa3b, v30
	v_mul_f32_e32 v31, 0x3fb8aa3b, v31
	v_mul_f32_e32 v32, 0x3fb8aa3b, v32
	v_mul_f32_e32 v33, 0x3fb8aa3b, v33
	v_mul_f32_e32 v34, 0x3fb8aa3b, v34
	v_mul_f32_e32 v35, 0x3fb8aa3b, v35
	v_add_f32_dpp v28, v28, v28 row_shr:1 row_mask:0xf bank_mask:0xf bound_ctrl:1
	v_add_f32_dpp v29, v29, v29 row_shr:1 row_mask:0xf bank_mask:0xf bound_ctrl:1
	v_add_f32_dpp v30, v30, v30 row_shr:1 row_mask:0xf bank_mask:0xf bound_ctrl:1
	v_add_f32_dpp v31, v31, v31 row_shr:1 row_mask:0xf bank_mask:0xf bound_ctrl:1
	v_add_f32_dpp v32, v32, v32 row_shr:1 row_mask:0xf bank_mask:0xf bound_ctrl:1
	v_add_f32_dpp v33, v33, v33 row_shr:1 row_mask:0xf bank_mask:0xf bound_ctrl:1
	v_add_f32_dpp v34, v34, v34 row_shr:1 row_mask:0xf bank_mask:0xf bound_ctrl:1
	v_add_f32_dpp v35, v35, v35 row_shr:1 row_mask:0xf bank_mask:0xf bound_ctrl:1
	v_add_f32_dpp v28, v28, v28 row_shr:2 row_mask:0xf bank_mask:0xf bound_ctrl:1
	v_add_f32_dpp v29, v29, v29 row_shr:2 row_mask:0xf bank_mask:0xf bound_ctrl:1
	v_add_f32_dpp v30, v30, v30 row_shr:2 row_mask:0xf bank_mask:0xf bound_ctrl:1
	v_add_f32_dpp v31, v31, v31 row_shr:2 row_mask:0xf bank_mask:0xf bound_ctrl:1
	v_add_f32_dpp v32, v32, v32 row_shr:2 row_mask:0xf bank_mask:0xf bound_ctrl:1
	v_add_f32_dpp v33, v33, v33 row_shr:2 row_mask:0xf bank_mask:0xf bound_ctrl:1
	v_add_f32_dpp v34, v34, v34 row_shr:2 row_mask:0xf bank_mask:0xf bound_ctrl:1
	v_add_f32_dpp v35, v35, v35 row_shr:2 row_mask:0xf bank_mask:0xf bound_ctrl:1
	v_add_f32_dpp v28, v28, v28 row_shr:4 row_mask:0xf bank_mask:0xf bound_ctrl:1
	v_add_f32_dpp v29, v29, v29 row_shr:4 row_mask:0xf bank_mask:0xf bound_ctrl:1
	v_add_f32_dpp v30, v30, v30 row_shr:4 row_mask:0xf bank_mask:0xf bound_ctrl:1
	v_add_f32_dpp v31, v31, v31 row_shr:4 row_mask:0xf bank_mask:0xf bound_ctrl:1
	v_add_f32_dpp v32, v32, v32 row_shr:4 row_mask:0xf bank_mask:0xf bound_ctrl:1
	v_add_f32_dpp v33, v33, v33 row_shr:4 row_mask:0xf bank_mask:0xf bound_ctrl:1
	v_add_f32_dpp v34, v34, v34 row_shr:4 row_mask:0xf bank_mask:0xf bound_ctrl:1
	v_add_f32_dpp v35, v35, v35 row_shr:4 row_mask:0xf bank_mask:0xf bound_ctrl:1
	v_add_f32_dpp v28, v28, v28 row_shr:8 row_mask:0xf bank_mask:0xf bound_ctrl:1
	v_add_f32_dpp v29, v29, v29 row_shr:8 row_mask:0xf bank_mask:0xf bound_ctrl:1
	v_add_f32_dpp v30, v30, v30 row_shr:8 row_mask:0xf bank_mask:0xf bound_ctrl:1
	v_add_f32_dpp v31, v31, v31 row_shr:8 row_mask:0xf bank_mask:0xf bound_ctrl:1
	v_add_f32_dpp v32, v32, v32 row_shr:8 row_mask:0xf bank_mask:0xf bound_ctrl:1
	v_add_f32_dpp v33, v33, v33 row_shr:8 row_mask:0xf bank_mask:0xf bound_ctrl:1
	v_add_f32_dpp v34, v34, v34 row_shr:8 row_mask:0xf bank_mask:0xf bound_ctrl:1
	v_add_f32_dpp v35, v35, v35 row_shr:8 row_mask:0xf bank_mask:0xf bound_ctrl:1
	v_add_f32_dpp v28, v28, v28 row_bcast:15 row_mask:0xa bank_mask:0xf
	v_add_f32_dpp v29, v29, v29 row_bcast:15 row_mask:0xa bank_mask:0xf
	v_add_f32_dpp v30, v30, v30 row_bcast:15 row_mask:0xa bank_mask:0xf
	v_add_f32_dpp v31, v31, v31 row_bcast:15 row_mask:0xa bank_mask:0xf
	v_add_f32_dpp v32, v32, v32 row_bcast:15 row_mask:0xa bank_mask:0xf
	v_add_f32_dpp v33, v33, v33 row_bcast:15 row_mask:0xa bank_mask:0xf
	v_add_f32_dpp v34, v34, v34 row_bcast:15 row_mask:0xa bank_mask:0xf
	v_add_f32_dpp v35, v35, v35 row_bcast:15 row_mask:0xa bank_mask:0xf
	v_add_f32_dpp v28, v28, v28 row_bcast:31 row_mask:0xc bank_mask:0xf
	v_add_f32_dpp v29, v29, v29 row_bcast:31 row_mask:0xc bank_mask:0xf
	v_add_f32_dpp v30, v30, v30 row_bcast:31 row_mask:0xc bank_mask:0xf
	v_add_f32_dpp v31, v31, v31 row_bcast:31 row_mask:0xc bank_mask:0xf
	v_add_f32_dpp v32, v32, v32 row_bcast:31 row_mask:0xc bank_mask:0xf
	v_add_f32_dpp v33, v33, v33 row_bcast:31 row_mask:0xc bank_mask:0xf
	v_add_f32_dpp v34, v34, v34 row_bcast:31 row_mask:0xc bank_mask:0xf
	v_add_f32_dpp v35, v35, v35 row_bcast:31 row_mask:0xc bank_mask:0xf
	v_exp_f32_e32 v36, v28
	v_lshlrev_b32_e32 v68, 16, v16
	v_and_b32_e32 v69, 0xffff0000, v16
	v_exp_f32_e32 v37, v29
	v_lshlrev_b32_e32 v70, 16, v17
	v_and_b32_e32 v71, 0xffff0000, v17
	v_exp_f32_e32 v38, v30
	v_lshlrev_b32_e32 v72, 16, v18
	v_and_b32_e32 v73, 0xffff0000, v18
	v_exp_f32_e32 v39, v31
	v_lshlrev_b32_e32 v74, 16, v19
	v_and_b32_e32 v75, 0xffff0000, v19
	v_exp_f32_e32 v40, v32
	v_lshlrev_b32_e32 v76, 16, v4
	v_and_b32_e32 v77, 0xffff0000, v4
	v_exp_f32_e32 v41, v33
	v_lshlrev_b32_e32 v78, 16, v5
	v_and_b32_e32 v79, 0xffff0000, v5
	v_exp_f32_e32 v42, v34
	v_lshlrev_b32_e32 v80, 16, v6
	v_and_b32_e32 v81, 0xffff0000, v6
	v_exp_f32_e32 v43, v35
	v_lshlrev_b32_e32 v82, 16, v7
	v_and_b32_e32 v83, 0xffff0000, v7
	v_exp_f32_e64 v44, -v28
	v_lshlrev_b32_e32 v84, 16, v20
	v_and_b32_e32 v85, 0xffff0000, v20
	v_exp_f32_e64 v45, -v29
	v_lshlrev_b32_e32 v86, 16, v21
	v_and_b32_e32 v87, 0xffff0000, v21
	v_exp_f32_e64 v46, -v30
	v_lshlrev_b32_e32 v88, 16, v22
	v_and_b32_e32 v89, 0xffff0000, v22
	v_exp_f32_e64 v47, -v31
	v_lshlrev_b32_e32 v90, 16, v23
	v_and_b32_e32 v91, 0xffff0000, v23
	v_exp_f32_e64 v48, -v32
	v_lshlrev_b32_e32 v92, 16, v8
	v_and_b32_e32 v93, 0xffff0000, v8
	v_exp_f32_e64 v49, -v33
	v_lshlrev_b32_e32 v94, 16, v9
	v_and_b32_e32 v95, 0xffff0000, v9
	v_exp_f32_e64 v50, -v34
	v_lshlrev_b32_e32 v96, 16, v10
	v_and_b32_e32 v97, 0xffff0000, v10
	v_exp_f32_e64 v51, -v35
	v_lshlrev_b32_e32 v98, 16, v11
	v_and_b32_e32 v99, 0xffff0000, v11
	v_mov_b32_dpp v212, v36 wave_shr:1 row_mask:0xf bank_mask:0xf
	v_mov_b32_dpp v213, v37 wave_shr:1 row_mask:0xf bank_mask:0xf
	v_mov_b32_dpp v214, v38 wave_shr:1 row_mask:0xf bank_mask:0xf
	v_mov_b32_dpp v215, v39 wave_shr:1 row_mask:0xf bank_mask:0xf
	v_mov_b32_dpp v216, v40 wave_shr:1 row_mask:0xf bank_mask:0xf
	v_mov_b32_dpp v217, v41 wave_shr:1 row_mask:0xf bank_mask:0xf
	v_mov_b32_dpp v218, v42 wave_shr:1 row_mask:0xf bank_mask:0xf
	v_mov_b32_dpp v219, v43 wave_shr:1 row_mask:0xf bank_mask:0xf
	v_readlane_b32 s8, v254, 60
	s_add_i32 s8, s8, 0x21c00
	v_mov_b32_e32 v0, s8
	s_mov_b64 s[22:23], exec
	s_andn2_b64 exec, exec, s[38:39]
	ds_write_b128 v0, v[36:39]
	ds_write_b128 v0, v[40:43] offset:16
	s_mov_b64 exec, s[22:23]
	v_pk_mul_f32 v[68:69], v[212:213], v[68:69] neg_lo:[0,1] neg_hi:[0,1]
	v_pk_mul_f32 v[70:71], v[214:215], v[70:71] neg_lo:[0,1] neg_hi:[0,1]
	v_pk_mul_f32 v[72:73], v[216:217], v[72:73] neg_lo:[0,1] neg_hi:[0,1]
	v_pk_mul_f32 v[74:75], v[218:219], v[74:75] neg_lo:[0,1] neg_hi:[0,1]
	v_pk_mul_f32 v[76:77], v[36:37], v[76:77]
	v_pk_mul_f32 v[78:79], v[38:39], v[78:79]
	v_pk_mul_f32 v[80:81], v[40:41], v[80:81]
	v_pk_mul_f32 v[82:83], v[42:43], v[82:83]
	v_pk_mul_f32 v[84:85], v[44:45], v[84:85]
	v_pk_mul_f32 v[86:87], v[46:47], v[86:87]
	v_pk_mul_f32 v[88:89], v[48:49], v[88:89]
	v_pk_mul_f32 v[90:91], v[50:51], v[90:91]
	v_pk_mul_f32 v[92:93], v[44:45], v[92:93]
	v_pk_mul_f32 v[94:95], v[46:47], v[94:95]
	v_pk_mul_f32 v[96:97], v[48:49], v[96:97]
	v_pk_mul_f32 v[98:99], v[50:51], v[98:99]
	v_cvt_pk_bf16_f32 v52, v68, v69
	v_cvt_pk_bf16_f32 v53, v70, v71
	v_cvt_pk_bf16_f32 v54, v72, v73
	v_cvt_pk_bf16_f32 v55, v74, v75
	v_cvt_pk_bf16_f32 v56, v76, v77
	v_cvt_pk_bf16_f32 v57, v78, v79
	v_cvt_pk_bf16_f32 v58, v80, v81
	v_cvt_pk_bf16_f32 v59, v82, v83
	s_add_i32 s91, s90, 1
	ds_write_b128 v142, v[52:55]
	ds_write_b128 v142, v[56:59] offset:27648
	v_cvt_pk_bf16_f32 v60, v84, v85
	v_cvt_pk_bf16_f32 v61, v86, v87
	v_cvt_pk_bf16_f32 v62, v88, v89
	v_cvt_pk_bf16_f32 v63, v90, v91
	v_cvt_pk_bf16_f32 v64, v92, v93
	v_cvt_pk_bf16_f32 v65, v94, v95
	v_cvt_pk_bf16_f32 v66, v96, v97
	v_cvt_pk_bf16_f32 v67, v98, v99
	s_cmp_ge_i32 s91, s88
	s_cselect_b64 s[22:23], -1, 0
	ds_write_b128 v142, v[60:63] offset:9216
	s_and_b64 vcc, exec, s[22:23]
	ds_write_b128 v142, v[64:67] offset:18432
	ds_write_b128 v142, v[12:15] offset:36864
	s_cbranch_vccnz .LBB0_877
	s_mul_hi_i32 s8, s91, 0x3e0f83e1
	s_mov_b64 s[94:95], s[20:21]
	s_mov_b64 s[20:21], s[68:69]
	s_mov_b64 s[68:69], s[66:67]
	s_mov_b64 s[66:67], s[64:65]
	s_mov_b64 s[64:65], s[62:63]
	s_mov_b64 s[62:63], s[18:19]
	s_mov_b64 s[18:19], s[46:47]
	s_mov_b64 s[46:47], s[44:45]
	s_mov_b64 s[44:45], s[42:43]
	s_mov_b64 s[42:43], s[40:41]
	s_mov_b64 s[40:41], s[38:39]
	s_lshr_b32 s9, s8, 31
	s_ashr_i32 s39, s8, 5
	s_add_i32 s39, s39, s9
	s_mul_i32 s8, s39, 0xffffff7c
	s_add_i32 vcc_lo, s90, s8
	s_add_i32 s34, vcc_lo, 1
	s_ashr_i32 s35, s39, 5
	s_and_b32 s38, s39, 1
	s_cmp_eq_u32 s38, 0
	s_cselect_b64 s[84:85], -1, 0
	s_cmp_gt_i32 s34, 3
	s_mov_b64 s[86:87], -1
	s_mul_i32 s8, s39, 0x84
	s_cbranch_scc0 .LBB0_874
	s_add_i32 s9, s27, s8
	s_add_i32 vcc_lo, vcc_lo, -3
	s_and_b64 s[86:87], s[84:85], exec
	s_cselect_b32 s9, vcc_lo, s9
	s_lshl_b32 s86, s35, 13
	s_lshl_b32 s9, s9, 6
	s_add_i32 s9, s9, s86
	s_mov_b64 s[86:87], 0
